# pipelined GEMM K-loops: the next stage's LDS-DMA pieces are issued two per MFMA group at the front of the stage (were one per group across the whole stage), giving the last pieces time to land before
# speedup vs baseline: 1.0194x; 1.0073x over previous
; template <int EPI, int MI>
; DI void gemm_tile(const GemmDesc& g, int tm, int tn, char* smem) {
;     ...
;   const int rowA = wm * (32 * MI) + r, rowB = wn * 64 + r;
;   const int hk = hh ^ ((r & 7) ^ ((r >> 3) & 3));
;     ...
;   G_GLDS(0, 0);
;   asm volatile("s_waitcnt vmcnt(0)" ::: "memory");
;   __syncthreads();
;   for (int kt = 0; kt < nk; kt += 2) {
;     if (kt + 1 < nk) G_GLDS(kt + 1, 1);
;     G_COMPUTE(0);
;     asm volatile("s_waitcnt vmcnt(0)" ::: "memory");
;     __syncthreads();
;     if (kt + 1 < nk) {
;       if (kt + 2 < nk) G_GLDS(kt + 2, 0);
;       G_COMPUTE(1);
;       asm volatile("s_waitcnt vmcnt(0)" ::: "memory");
;       __syncthreads();
;     }
;   }
.Lga_loop:
	ds_read_b128 v[232:235], v162 offset:8192
	s_waitcnt lgkmcnt(2)
	v_mfma_f32_32x32x16_bf16 v[80:95], v[224:227], v[236:239], v[80:95]
	v_mfma_f32_32x32x16_bf16 v[64:79], v[224:227], v[240:243], v[64:79]
	s_add_u32 m0, s100, 0x6000
	v_lshl_add_u64 v[106:107], v[174:175], 0, s[96:97]
	global_load_lds_dwordx4 v[106:107], off
	s_add_u32 m0, s100, 0x7000
	v_lshl_add_u64 v[106:107], v[174:175], 0, s[50:51]
	global_load_lds_dwordx4 v[106:107], off
	ds_read_b128 v[244:247], v167 offset:49152
	ds_read_b128 v[248:251], v167 offset:53248
	ds_read_b128 v[224:227], v163
	s_waitcnt lgkmcnt(4)
	v_mfma_f32_32x32x16_bf16 v[48:63], v[228:231], v[236:239], v[48:63]
	v_mfma_f32_32x32x16_bf16 v[32:47], v[228:231], v[240:243], v[32:47]
	s_add_u32 m0, s100, 0x8000
	v_lshl_add_u64 v[106:107], v[174:175], 0, s[24:25]
	global_load_lds_dwordx4 v[106:107], off
	s_add_u32 m0, s100, 0x9000
	v_lshl_add_u64 v[106:107], v[174:175], 0, s[26:27]
	global_load_lds_dwordx4 v[106:107], off
	ds_read_b128 v[228:231], v163 offset:4096
	s_waitcnt lgkmcnt(4)
	v_mfma_f32_32x32x16_bf16 v[16:31], v[232:235], v[236:239], v[16:31]
	v_mfma_f32_32x32x16_bf16 v[0:15], v[232:235], v[240:243], v[0:15]
	s_add_u32 m0, s100, 0xa000
	v_lshl_add_u64 v[106:107], v[174:175], 0, s[28:29]
	global_load_lds_dwordx4 v[106:107], off
	s_add_u32 m0, s100, 0xb000
	v_lshl_add_u64 v[106:107], v[174:175], 0, s[30:31]
	global_load_lds_dwordx4 v[106:107], off
	v_lshl_add_u64 v[174:175], v[174:175], 0, s[18:19]
	ds_read_b128 v[232:235], v163 offset:8192
	s_waitcnt lgkmcnt(2)
	v_mfma_f32_32x32x16_bf16 v[80:95], v[224:227], v[244:247], v[80:95]
	v_mfma_f32_32x32x16_bf16 v[64:79], v[224:227], v[248:251], v[64:79]
	s_add_u32 m0, s100, 0x10000
	v_lshl_add_u64 v[106:107], v[176:177], 0, s[18:19]
	global_load_lds_dwordx4 v[106:107], off
	s_add_u32 m0, s100, 0x11000
	v_lshl_add_u64 v[106:107], v[176:177], 0, s[42:43]
	global_load_lds_dwordx4 v[106:107], off
	ds_read_b128 v[236:239], v168 offset:49152
	ds_read_b128 v[240:243], v168 offset:53248
	ds_read_b128 v[224:227], v164
	s_waitcnt lgkmcnt(4)
	v_mfma_f32_32x32x16_bf16 v[48:63], v[228:231], v[244:247], v[48:63]
	v_mfma_f32_32x32x16_bf16 v[32:47], v[228:231], v[248:251], v[32:47]
	s_mov_b64 s[16:17], 0x20080
	s_add_u32 m0, s100, 0x12000
	v_lshl_add_u64 v[106:107], v[176:177], 0, s[16:17]
	global_load_lds_dwordx4 v[106:107], off
	s_mov_b64 s[16:17], 0x30080
	s_add_u32 m0, s100, 0x13000
	v_lshl_add_u64 v[106:107], v[176:177], 0, s[16:17]
	global_load_lds_dwordx4 v[106:107], off
	v_lshl_add_u64 v[176:177], v[176:177], 0, s[18:19]
	ds_read_b128 v[228:231], v164 offset:4096
	s_waitcnt lgkmcnt(4)
	v_mfma_f32_32x32x16_bf16 v[16:31], v[232:235], v[244:247], v[16:31]
	v_mfma_f32_32x32x16_bf16 v[0:15], v[232:235], v[248:251], v[0:15]
	ds_read_b128 v[232:235], v164 offset:8192
	s_waitcnt lgkmcnt(2)
	v_mfma_f32_32x32x16_bf16 v[80:95], v[224:227], v[236:239], v[80:95]
	v_mfma_f32_32x32x16_bf16 v[64:79], v[224:227], v[240:243], v[64:79]
	ds_read_b128 v[244:247], v169 offset:49152
	ds_read_b128 v[248:251], v169 offset:53248
	ds_read_b128 v[224:227], v165
	s_waitcnt lgkmcnt(4)
	v_mfma_f32_32x32x16_bf16 v[48:63], v[228:231], v[236:239], v[48:63]
	v_mfma_f32_32x32x16_bf16 v[32:47], v[228:231], v[240:243], v[32:47]
	ds_read_b128 v[228:231], v165 offset:4096
	s_waitcnt lgkmcnt(4)
	v_mfma_f32_32x32x16_bf16 v[16:31], v[232:235], v[236:239], v[16:31]
	v_mfma_f32_32x32x16_bf16 v[0:15], v[232:235], v[240:243], v[0:15]
	ds_read_b128 v[232:235], v165 offset:8192
	s_waitcnt lgkmcnt(2)
	v_mfma_f32_32x32x16_bf16 v[80:95], v[224:227], v[244:247], v[80:95]
	v_mfma_f32_32x32x16_bf16 v[64:79], v[224:227], v[248:251], v[64:79]
	s_waitcnt lgkmcnt(0)
	s_waitcnt vmcnt(0)
	s_barrier
	ds_read_b128 v[236:239], v170
	ds_read_b128 v[240:243], v170 offset:4096
	ds_read_b128 v[224:227], v162 offset:24576
	v_mfma_f32_32x32x16_bf16 v[48:63], v[228:231], v[244:247], v[48:63]
	v_mfma_f32_32x32x16_bf16 v[32:47], v[228:231], v[248:251], v[32:47]
	ds_read_b128 v[228:231], v162 offset:28672
	v_mfma_f32_32x32x16_bf16 v[16:31], v[232:235], v[244:247], v[16:31]
	v_mfma_f32_32x32x16_bf16 v[0:15], v[232:235], v[248:251], v[0:15]
	s_cmp_eq_u32 s15, 14
	s_cbranch_scc1 .Lga_last
; template <int EPI, int MI>
; DI void gemm_tile(const GemmDesc& g, int tm, int tn, char* smem) {
;     ...
;   const int rowA = wm * (32 * MI) + r, rowB = wn * 64 + r;
;   const int hk = hh ^ ((r & 7) ^ ((r >> 3) & 3));
;     ...
;   G_GLDS(0, 0);
;   asm volatile("s_waitcnt vmcnt(0)" ::: "memory");
;   __syncthreads();
;   for (int kt = 0; kt < nk; kt += 2) {
;     if (kt + 1 < nk) G_GLDS(kt + 1, 1);
;     G_COMPUTE(0);
;     asm volatile("s_waitcnt vmcnt(0)" ::: "memory");
;     __syncthreads();
;     if (kt + 1 < nk) {
;       if (kt + 2 < nk) G_GLDS(kt + 2, 0);
;       G_COMPUTE(1);
;       asm volatile("s_waitcnt vmcnt(0)" ::: "memory");
;       __syncthreads();
;     }
;   }
	ds_read_b128 v[232:235], v162 offset:32768
	s_waitcnt lgkmcnt(2)
	v_mfma_f32_32x32x16_bf16 v[80:95], v[224:227], v[236:239], v[80:95]
	v_mfma_f32_32x32x16_bf16 v[64:79], v[224:227], v[240:243], v[64:79]
	s_mov_b32 m0, s100
	v_lshl_add_u64 v[106:107], v[174:175], 0, s[96:97]
	global_load_lds_dwordx4 v[106:107], off
	s_add_u32 m0, s100, 0x1000
	v_lshl_add_u64 v[106:107], v[174:175], 0, s[50:51]
	global_load_lds_dwordx4 v[106:107], off
	ds_read_b128 v[244:247], v171
	ds_read_b128 v[248:251], v171 offset:4096
	ds_read_b128 v[224:227], v163 offset:24576
	s_waitcnt lgkmcnt(4)
	v_mfma_f32_32x32x16_bf16 v[48:63], v[228:231], v[236:239], v[48:63]
	v_mfma_f32_32x32x16_bf16 v[32:47], v[228:231], v[240:243], v[32:47]
	s_add_u32 m0, s100, 0x2000
	v_lshl_add_u64 v[106:107], v[174:175], 0, s[24:25]
	global_load_lds_dwordx4 v[106:107], off
	s_add_u32 m0, s100, 0x3000
	v_lshl_add_u64 v[106:107], v[174:175], 0, s[26:27]
	global_load_lds_dwordx4 v[106:107], off
	ds_read_b128 v[228:231], v163 offset:28672
	s_waitcnt lgkmcnt(4)
	v_mfma_f32_32x32x16_bf16 v[16:31], v[232:235], v[236:239], v[16:31]
	v_mfma_f32_32x32x16_bf16 v[0:15], v[232:235], v[240:243], v[0:15]
	s_add_u32 m0, s100, 0x4000
	v_lshl_add_u64 v[106:107], v[174:175], 0, s[28:29]
	global_load_lds_dwordx4 v[106:107], off
	s_add_u32 m0, s100, 0x5000
	v_lshl_add_u64 v[106:107], v[174:175], 0, s[30:31]
	global_load_lds_dwordx4 v[106:107], off
	v_lshl_add_u64 v[174:175], v[174:175], 0, s[18:19]
	ds_read_b128 v[232:235], v163 offset:32768
	s_waitcnt lgkmcnt(2)
	v_mfma_f32_32x32x16_bf16 v[80:95], v[224:227], v[244:247], v[80:95]
	v_mfma_f32_32x32x16_bf16 v[64:79], v[224:227], v[248:251], v[64:79]
	s_add_u32 m0, s100, 0xc000
	v_lshl_add_u64 v[106:107], v[176:177], 0, s[18:19]
	global_load_lds_dwordx4 v[106:107], off
	s_add_u32 m0, s100, 0xd000
	v_lshl_add_u64 v[106:107], v[176:177], 0, s[42:43]
	global_load_lds_dwordx4 v[106:107], off
	ds_read_b128 v[236:239], v172
	ds_read_b128 v[240:243], v172 offset:4096
	ds_read_b128 v[224:227], v164 offset:24576
	s_waitcnt lgkmcnt(4)
	v_mfma_f32_32x32x16_bf16 v[48:63], v[228:231], v[244:247], v[48:63]
	v_mfma_f32_32x32x16_bf16 v[32:47], v[228:231], v[248:251], v[32:47]
	s_mov_b64 s[16:17], 0x20080
	s_add_u32 m0, s100, 0xe000
	v_lshl_add_u64 v[106:107], v[176:177], 0, s[16:17]
	global_load_lds_dwordx4 v[106:107], off
	s_mov_b64 s[16:17], 0x30080
	s_add_u32 m0, s100, 0xf000
	v_lshl_add_u64 v[106:107], v[176:177], 0, s[16:17]
	global_load_lds_dwordx4 v[106:107], off
	v_lshl_add_u64 v[176:177], v[176:177], 0, s[18:19]
	ds_read_b128 v[228:231], v164 offset:28672
	s_waitcnt lgkmcnt(4)
	v_mfma_f32_32x32x16_bf16 v[16:31], v[232:235], v[244:247], v[16:31]
	v_mfma_f32_32x32x16_bf16 v[0:15], v[232:235], v[248:251], v[0:15]
	ds_read_b128 v[232:235], v164 offset:32768
	s_waitcnt lgkmcnt(2)
	v_mfma_f32_32x32x16_bf16 v[80:95], v[224:227], v[236:239], v[80:95]
	v_mfma_f32_32x32x16_bf16 v[64:79], v[224:227], v[240:243], v[64:79]
	ds_read_b128 v[244:247], v173
	ds_read_b128 v[248:251], v173 offset:4096
	ds_read_b128 v[224:227], v165 offset:24576
	s_waitcnt lgkmcnt(4)
	v_mfma_f32_32x32x16_bf16 v[48:63], v[228:231], v[236:239], v[48:63]
	v_mfma_f32_32x32x16_bf16 v[32:47], v[228:231], v[240:243], v[32:47]
	ds_read_b128 v[228:231], v165 offset:28672
	s_waitcnt lgkmcnt(4)
	v_mfma_f32_32x32x16_bf16 v[16:31], v[232:235], v[236:239], v[16:31]
	v_mfma_f32_32x32x16_bf16 v[0:15], v[232:235], v[240:243], v[0:15]
	ds_read_b128 v[232:235], v165 offset:32768
	s_waitcnt lgkmcnt(2)
	v_mfma_f32_32x32x16_bf16 v[80:95], v[224:227], v[244:247], v[80:95]
	v_mfma_f32_32x32x16_bf16 v[64:79], v[224:227], v[248:251], v[64:79]
	s_waitcnt lgkmcnt(0)
	s_waitcnt vmcnt(0)
	s_barrier
	ds_read_b128 v[236:239], v166 offset:49152
	ds_read_b128 v[240:243], v166 offset:53248
	ds_read_b128 v[224:227], v162
	v_mfma_f32_32x32x16_bf16 v[48:63], v[228:231], v[244:247], v[48:63]
	v_mfma_f32_32x32x16_bf16 v[32:47], v[228:231], v[248:251], v[32:47]
	ds_read_b128 v[228:231], v162 offset:4096
	v_mfma_f32_32x32x16_bf16 v[16:31], v[232:235], v[244:247], v[16:31]
	v_mfma_f32_32x32x16_bf16 v[0:15], v[232:235], v[248:251], v[0:15]
	s_add_u32 s15, s15, 2
	s_branch .Lga_loop

; template <int EPI, int MI>
; DI void gemm_tile(const GemmDesc& g, int tm, int tn, char* smem) {
;     ...
;   const int rowA = wm * (32 * MI) + r, rowB = wn * 64 + r;
;   const int hk = hh ^ ((r & 7) ^ ((r >> 3) & 3));
;     ...
;   G_GLDS(0, 0);
;   asm volatile("s_waitcnt vmcnt(0)" ::: "memory");
;   __syncthreads();
;   for (int kt = 0; kt < nk; kt += 2) {
;     if (kt + 1 < nk) G_GLDS(kt + 1, 1);
;     G_COMPUTE(0);
;     asm volatile("s_waitcnt vmcnt(0)" ::: "memory");
;     __syncthreads();
;     if (kt + 1 < nk) {
;       if (kt + 2 < nk) G_GLDS(kt + 2, 0);
;       G_COMPUTE(1);
;       asm volatile("s_waitcnt vmcnt(0)" ::: "memory");
;       __syncthreads();
;     }
;   }
.Lgd_loop:
	ds_read_b128 v[232:235], v162 offset:8192
	s_waitcnt lgkmcnt(2)
	v_mfma_f32_32x32x16_bf16 v[80:95], v[224:227], v[236:239], v[80:95]
	v_mfma_f32_32x32x16_bf16 v[64:79], v[224:227], v[240:243], v[64:79]
	s_mov_b64 s[16:17], 0x5872080
	s_add_u32 m0, s100, 0x6000
	v_lshl_add_u64 v[106:107], v[252:253], 0, s[16:17]
	global_load_lds_dwordx4 v[106:107], off
	s_mov_b64 s[16:17], 0x589e080
	s_add_u32 m0, s100, 0x7000
	v_lshl_add_u64 v[106:107], v[252:253], 0, s[16:17]
	global_load_lds_dwordx4 v[106:107], off
	ds_read_b128 v[244:247], v167 offset:49152
	ds_read_b128 v[248:251], v167 offset:53248
	ds_read_b128 v[224:227], v163
	s_waitcnt lgkmcnt(4)
	v_mfma_f32_32x32x16_bf16 v[48:63], v[228:231], v[236:239], v[48:63]
	v_mfma_f32_32x32x16_bf16 v[32:47], v[228:231], v[240:243], v[32:47]
	s_mov_b64 s[16:17], 0x58ca080
	s_add_u32 m0, s100, 0x8000
	v_lshl_add_u64 v[106:107], v[252:253], 0, s[16:17]
	global_load_lds_dwordx4 v[106:107], off
	s_mov_b64 s[16:17], 0x58f6080
	s_add_u32 m0, s100, 0x9000
	v_lshl_add_u64 v[106:107], v[252:253], 0, s[16:17]
	global_load_lds_dwordx4 v[106:107], off
	ds_read_b128 v[228:231], v163 offset:4096
	s_waitcnt lgkmcnt(4)
	v_mfma_f32_32x32x16_bf16 v[16:31], v[232:235], v[236:239], v[16:31]
	v_mfma_f32_32x32x16_bf16 v[0:15], v[232:235], v[240:243], v[0:15]
	s_mov_b64 s[16:17], 0x5922080
	s_add_u32 m0, s100, 0xa000
	v_lshl_add_u64 v[106:107], v[252:253], 0, s[16:17]
	global_load_lds_dwordx4 v[106:107], off
	s_mov_b64 s[16:17], 0x594e080
	s_add_u32 m0, s100, 0xb000
	v_lshl_add_u64 v[106:107], v[252:253], 0, s[16:17]
	global_load_lds_dwordx4 v[106:107], off
	v_lshl_add_u64 v[252:253], v[252:253], 0, s[4:5]
	ds_read_b128 v[232:235], v163 offset:8192
	s_waitcnt lgkmcnt(2)
	v_mfma_f32_32x32x16_bf16 v[80:95], v[224:227], v[244:247], v[80:95]
	v_mfma_f32_32x32x16_bf16 v[64:79], v[224:227], v[248:251], v[64:79]
	s_mov_b64 s[16:17], 0x1600080
	s_add_u32 m0, s100, 0x10000
	v_lshl_add_u64 v[106:107], v[254:255], 0, s[16:17]
	global_load_lds_dwordx4 v[106:107], off
	s_mov_b64 s[16:17], 0x162c080
	s_add_u32 m0, s100, 0x11000
	v_lshl_add_u64 v[106:107], v[254:255], 0, s[16:17]
	global_load_lds_dwordx4 v[106:107], off
	ds_read_b128 v[236:239], v168 offset:49152
	ds_read_b128 v[240:243], v168 offset:53248
	ds_read_b128 v[224:227], v164
	s_waitcnt lgkmcnt(4)
	v_mfma_f32_32x32x16_bf16 v[48:63], v[228:231], v[244:247], v[48:63]
	v_mfma_f32_32x32x16_bf16 v[32:47], v[228:231], v[248:251], v[32:47]
	s_mov_b64 s[16:17], 0x1658080
	s_add_u32 m0, s100, 0x12000
	v_lshl_add_u64 v[106:107], v[254:255], 0, s[16:17]
	global_load_lds_dwordx4 v[106:107], off
	s_mov_b64 s[16:17], 0x1684080
	s_add_u32 m0, s100, 0x13000
	v_lshl_add_u64 v[106:107], v[254:255], 0, s[16:17]
	global_load_lds_dwordx4 v[106:107], off
	v_lshl_add_u64 v[254:255], v[254:255], 0, s[4:5]
	ds_read_b128 v[228:231], v164 offset:4096
	s_waitcnt lgkmcnt(4)
	v_mfma_f32_32x32x16_bf16 v[16:31], v[232:235], v[244:247], v[16:31]
	v_mfma_f32_32x32x16_bf16 v[0:15], v[232:235], v[248:251], v[0:15]
	ds_read_b128 v[232:235], v164 offset:8192
	s_waitcnt lgkmcnt(2)
	v_mfma_f32_32x32x16_bf16 v[80:95], v[224:227], v[236:239], v[80:95]
	v_mfma_f32_32x32x16_bf16 v[64:79], v[224:227], v[240:243], v[64:79]
	ds_read_b128 v[244:247], v169 offset:49152
	ds_read_b128 v[248:251], v169 offset:53248
	ds_read_b128 v[224:227], v165
	s_waitcnt lgkmcnt(4)
	v_mfma_f32_32x32x16_bf16 v[48:63], v[228:231], v[236:239], v[48:63]
	v_mfma_f32_32x32x16_bf16 v[32:47], v[228:231], v[240:243], v[32:47]
	ds_read_b128 v[228:231], v165 offset:4096
	s_waitcnt lgkmcnt(4)
	v_mfma_f32_32x32x16_bf16 v[16:31], v[232:235], v[236:239], v[16:31]
	v_mfma_f32_32x32x16_bf16 v[0:15], v[232:235], v[240:243], v[0:15]
	ds_read_b128 v[232:235], v165 offset:8192
	s_waitcnt lgkmcnt(2)
	v_mfma_f32_32x32x16_bf16 v[80:95], v[224:227], v[244:247], v[80:95]
	v_mfma_f32_32x32x16_bf16 v[64:79], v[224:227], v[248:251], v[64:79]
	s_waitcnt lgkmcnt(0)
	s_waitcnt vmcnt(0)
	s_barrier
	ds_read_b128 v[236:239], v170
	ds_read_b128 v[240:243], v170 offset:4096
	ds_read_b128 v[224:227], v162 offset:24576
	v_mfma_f32_32x32x16_bf16 v[48:63], v[228:231], v[244:247], v[48:63]
	v_mfma_f32_32x32x16_bf16 v[32:47], v[228:231], v[248:251], v[32:47]
	ds_read_b128 v[228:231], v162 offset:28672
	v_mfma_f32_32x32x16_bf16 v[16:31], v[232:235], v[244:247], v[16:31]
	v_mfma_f32_32x32x16_bf16 v[0:15], v[232:235], v[248:251], v[0:15]
	s_cmp_eq_u32 s15, 42
	s_cbranch_scc1 .Lgd_last
; template <int EPI, int MI>
; DI void gemm_tile(const GemmDesc& g, int tm, int tn, char* smem) {
;     ...
;   const int rowA = wm * (32 * MI) + r, rowB = wn * 64 + r;
;   const int hk = hh ^ ((r & 7) ^ ((r >> 3) & 3));
;     ...
;   G_GLDS(0, 0);
;   asm volatile("s_waitcnt vmcnt(0)" ::: "memory");
;   __syncthreads();
;   for (int kt = 0; kt < nk; kt += 2) {
;     if (kt + 1 < nk) G_GLDS(kt + 1, 1);
;     G_COMPUTE(0);
;     asm volatile("s_waitcnt vmcnt(0)" ::: "memory");
;     __syncthreads();
;     if (kt + 1 < nk) {
;       if (kt + 2 < nk) G_GLDS(kt + 2, 0);
;       G_COMPUTE(1);
;       asm volatile("s_waitcnt vmcnt(0)" ::: "memory");
;       __syncthreads();
;     }
;   }
	ds_read_b128 v[232:235], v162 offset:32768
	s_waitcnt lgkmcnt(2)
	v_mfma_f32_32x32x16_bf16 v[80:95], v[224:227], v[236:239], v[80:95]
	v_mfma_f32_32x32x16_bf16 v[64:79], v[224:227], v[240:243], v[64:79]
	s_mov_b64 s[16:17], 0x5872080
	s_mov_b32 m0, s100
	v_lshl_add_u64 v[106:107], v[252:253], 0, s[16:17]
	global_load_lds_dwordx4 v[106:107], off
	s_mov_b64 s[16:17], 0x589e080
	s_add_u32 m0, s100, 0x1000
	v_lshl_add_u64 v[106:107], v[252:253], 0, s[16:17]
	global_load_lds_dwordx4 v[106:107], off
	ds_read_b128 v[244:247], v171
	ds_read_b128 v[248:251], v171 offset:4096
	ds_read_b128 v[224:227], v163 offset:24576
	s_waitcnt lgkmcnt(4)
	v_mfma_f32_32x32x16_bf16 v[48:63], v[228:231], v[236:239], v[48:63]
	v_mfma_f32_32x32x16_bf16 v[32:47], v[228:231], v[240:243], v[32:47]
	s_mov_b64 s[16:17], 0x58ca080
	s_add_u32 m0, s100, 0x2000
	v_lshl_add_u64 v[106:107], v[252:253], 0, s[16:17]
	global_load_lds_dwordx4 v[106:107], off
	s_mov_b64 s[16:17], 0x58f6080
	s_add_u32 m0, s100, 0x3000
	v_lshl_add_u64 v[106:107], v[252:253], 0, s[16:17]
	global_load_lds_dwordx4 v[106:107], off
	ds_read_b128 v[228:231], v163 offset:28672
	s_waitcnt lgkmcnt(4)
	v_mfma_f32_32x32x16_bf16 v[16:31], v[232:235], v[236:239], v[16:31]
	v_mfma_f32_32x32x16_bf16 v[0:15], v[232:235], v[240:243], v[0:15]
	s_mov_b64 s[16:17], 0x5922080
	s_add_u32 m0, s100, 0x4000
	v_lshl_add_u64 v[106:107], v[252:253], 0, s[16:17]
	global_load_lds_dwordx4 v[106:107], off
	s_mov_b64 s[16:17], 0x594e080
	s_add_u32 m0, s100, 0x5000
	v_lshl_add_u64 v[106:107], v[252:253], 0, s[16:17]
	global_load_lds_dwordx4 v[106:107], off
	v_lshl_add_u64 v[252:253], v[252:253], 0, s[4:5]
	ds_read_b128 v[232:235], v163 offset:32768
	s_waitcnt lgkmcnt(2)
	v_mfma_f32_32x32x16_bf16 v[80:95], v[224:227], v[244:247], v[80:95]
	v_mfma_f32_32x32x16_bf16 v[64:79], v[224:227], v[248:251], v[64:79]
	s_mov_b64 s[16:17], 0x1600080
	s_add_u32 m0, s100, 0xc000
	v_lshl_add_u64 v[106:107], v[254:255], 0, s[16:17]
	global_load_lds_dwordx4 v[106:107], off
	s_mov_b64 s[16:17], 0x162c080
	s_add_u32 m0, s100, 0xd000
	v_lshl_add_u64 v[106:107], v[254:255], 0, s[16:17]
	global_load_lds_dwordx4 v[106:107], off
	ds_read_b128 v[236:239], v172
	ds_read_b128 v[240:243], v172 offset:4096
	ds_read_b128 v[224:227], v164 offset:24576
	s_waitcnt lgkmcnt(4)
	v_mfma_f32_32x32x16_bf16 v[48:63], v[228:231], v[244:247], v[48:63]
	v_mfma_f32_32x32x16_bf16 v[32:47], v[228:231], v[248:251], v[32:47]
	s_mov_b64 s[16:17], 0x1658080
	s_add_u32 m0, s100, 0xe000
	v_lshl_add_u64 v[106:107], v[254:255], 0, s[16:17]
	global_load_lds_dwordx4 v[106:107], off
	s_mov_b64 s[16:17], 0x1684080
	s_add_u32 m0, s100, 0xf000
	v_lshl_add_u64 v[106:107], v[254:255], 0, s[16:17]
	global_load_lds_dwordx4 v[106:107], off
	v_lshl_add_u64 v[254:255], v[254:255], 0, s[4:5]
	ds_read_b128 v[228:231], v164 offset:28672
	s_waitcnt lgkmcnt(4)
	v_mfma_f32_32x32x16_bf16 v[16:31], v[232:235], v[244:247], v[16:31]
	v_mfma_f32_32x32x16_bf16 v[0:15], v[232:235], v[248:251], v[0:15]
	ds_read_b128 v[232:235], v164 offset:32768
	s_waitcnt lgkmcnt(2)
	v_mfma_f32_32x32x16_bf16 v[80:95], v[224:227], v[236:239], v[80:95]
	v_mfma_f32_32x32x16_bf16 v[64:79], v[224:227], v[240:243], v[64:79]
	ds_read_b128 v[244:247], v173
	ds_read_b128 v[248:251], v173 offset:4096
	ds_read_b128 v[224:227], v165 offset:24576
	s_waitcnt lgkmcnt(4)
	v_mfma_f32_32x32x16_bf16 v[48:63], v[228:231], v[236:239], v[48:63]
	v_mfma_f32_32x32x16_bf16 v[32:47], v[228:231], v[240:243], v[32:47]
	ds_read_b128 v[228:231], v165 offset:28672
	s_waitcnt lgkmcnt(4)
	v_mfma_f32_32x32x16_bf16 v[16:31], v[232:235], v[236:239], v[16:31]
	v_mfma_f32_32x32x16_bf16 v[0:15], v[232:235], v[240:243], v[0:15]
	ds_read_b128 v[232:235], v165 offset:32768
	s_waitcnt lgkmcnt(2)
	v_mfma_f32_32x32x16_bf16 v[80:95], v[224:227], v[244:247], v[80:95]
	v_mfma_f32_32x32x16_bf16 v[64:79], v[224:227], v[248:251], v[64:79]
	s_waitcnt lgkmcnt(0)
	s_waitcnt vmcnt(0)
	s_barrier
	ds_read_b128 v[236:239], v166 offset:49152
	ds_read_b128 v[240:243], v166 offset:53248
	ds_read_b128 v[224:227], v162
	v_mfma_f32_32x32x16_bf16 v[48:63], v[228:231], v[244:247], v[48:63]
	v_mfma_f32_32x32x16_bf16 v[32:47], v[228:231], v[248:251], v[32:47]
	ds_read_b128 v[228:231], v162 offset:4096
	v_mfma_f32_32x32x16_bf16 v[16:31], v[232:235], v[244:247], v[16:31]
	v_mfma_f32_32x32x16_bf16 v[0:15], v[232:235], v[248:251], v[0:15]
	s_add_u32 s15, s15, 2
	s_branch .Lgd_loop

; template <int EPI, int MI>
; DI void gemm_tile(const GemmDesc& g, int tm, int tn, char* smem) {
;     ...
;   const int rowA = wm * (32 * MI) + r, rowB = wn * 64 + r;
;   const int hk = hh ^ ((r & 7) ^ ((r >> 3) & 3));
;     ...
;   G_GLDS(0, 0);
;   asm volatile("s_waitcnt vmcnt(0)" ::: "memory");
;   __syncthreads();
;   for (int kt = 0; kt < nk; kt += 2) {
;     if (kt + 1 < nk) G_GLDS(kt + 1, 1);
;     G_COMPUTE(0);
;     asm volatile("s_waitcnt vmcnt(0)" ::: "memory");
;     __syncthreads();
;     if (kt + 1 < nk) {
;       if (kt + 2 < nk) G_GLDS(kt + 2, 0);
;       G_COMPUTE(1);
;       asm volatile("s_waitcnt vmcnt(0)" ::: "memory");
;       __syncthreads();
;     }
;   }
.Lgw_loop:
	ds_read_b128 v[232:235], v162 offset:8192
	s_waitcnt lgkmcnt(2)
	v_mfma_f32_32x32x16_bf16 v[80:95], v[224:227], v[236:239], v[80:95]
	v_mfma_f32_32x32x16_bf16 v[64:79], v[224:227], v[240:243], v[64:79]
	s_add_u32 m0, s100, 0x6000
	v_lshl_add_u64 v[106:107], v[252:253], 0, s[96:97]
	global_load_lds_dwordx4 v[106:107], off
	s_add_u32 m0, s100, 0x7000
	v_lshl_add_u64 v[106:107], v[252:253], 0, s[50:51]
	global_load_lds_dwordx4 v[106:107], off
	ds_read_b128 v[244:247], v167 offset:49152
	ds_read_b128 v[248:251], v167 offset:53248
	ds_read_b128 v[224:227], v163
	s_waitcnt lgkmcnt(4)
	v_mfma_f32_32x32x16_bf16 v[48:63], v[228:231], v[236:239], v[48:63]
	v_mfma_f32_32x32x16_bf16 v[32:47], v[228:231], v[240:243], v[32:47]
	s_add_u32 m0, s100, 0x8000
	v_lshl_add_u64 v[106:107], v[252:253], 0, s[24:25]
	global_load_lds_dwordx4 v[106:107], off
	s_add_u32 m0, s100, 0x9000
	v_lshl_add_u64 v[106:107], v[252:253], 0, s[26:27]
	global_load_lds_dwordx4 v[106:107], off
	ds_read_b128 v[228:231], v163 offset:4096
	s_waitcnt lgkmcnt(4)
	v_mfma_f32_32x32x16_bf16 v[16:31], v[232:235], v[236:239], v[16:31]
	v_mfma_f32_32x32x16_bf16 v[0:15], v[232:235], v[240:243], v[0:15]
	s_add_u32 m0, s100, 0xa000
	v_lshl_add_u64 v[106:107], v[252:253], 0, s[28:29]
	global_load_lds_dwordx4 v[106:107], off
	s_add_u32 m0, s100, 0xb000
	v_lshl_add_u64 v[106:107], v[252:253], 0, s[30:31]
	global_load_lds_dwordx4 v[106:107], off
	v_lshl_add_u64 v[252:253], v[252:253], 0, s[0:1]
	ds_read_b128 v[232:235], v163 offset:8192
	s_waitcnt lgkmcnt(2)
	v_mfma_f32_32x32x16_bf16 v[80:95], v[224:227], v[244:247], v[80:95]
	v_mfma_f32_32x32x16_bf16 v[64:79], v[224:227], v[248:251], v[64:79]
	s_mov_b64 s[16:17], 0x2100080
	s_add_u32 m0, s100, 0x10000
	v_lshl_add_u64 v[106:107], v[254:255], 0, s[16:17]
	global_load_lds_dwordx4 v[106:107], off
	s_mov_b64 s[16:17], 0x2110080
	s_add_u32 m0, s100, 0x11000
	v_lshl_add_u64 v[106:107], v[254:255], 0, s[16:17]
	global_load_lds_dwordx4 v[106:107], off
	ds_read_b128 v[236:239], v168 offset:49152
	ds_read_b128 v[240:243], v168 offset:53248
	ds_read_b128 v[224:227], v164
	s_waitcnt lgkmcnt(4)
	v_mfma_f32_32x32x16_bf16 v[48:63], v[228:231], v[244:247], v[48:63]
	v_mfma_f32_32x32x16_bf16 v[32:47], v[228:231], v[248:251], v[32:47]
	s_mov_b64 s[16:17], 0x2120080
	s_add_u32 m0, s100, 0x12000
	v_lshl_add_u64 v[106:107], v[254:255], 0, s[16:17]
	global_load_lds_dwordx4 v[106:107], off
	s_mov_b64 s[16:17], 0x2130080
	s_add_u32 m0, s100, 0x13000
	v_lshl_add_u64 v[106:107], v[254:255], 0, s[16:17]
	global_load_lds_dwordx4 v[106:107], off
	v_lshl_add_u64 v[254:255], v[254:255], 0, s[0:1]
	ds_read_b128 v[228:231], v164 offset:4096
	s_waitcnt lgkmcnt(4)
	v_mfma_f32_32x32x16_bf16 v[16:31], v[232:235], v[244:247], v[16:31]
	v_mfma_f32_32x32x16_bf16 v[0:15], v[232:235], v[248:251], v[0:15]
	ds_read_b128 v[232:235], v164 offset:8192
	s_waitcnt lgkmcnt(2)
	v_mfma_f32_32x32x16_bf16 v[80:95], v[224:227], v[236:239], v[80:95]
	v_mfma_f32_32x32x16_bf16 v[64:79], v[224:227], v[240:243], v[64:79]
	ds_read_b128 v[244:247], v169 offset:49152
	ds_read_b128 v[248:251], v169 offset:53248
	ds_read_b128 v[224:227], v165
	s_waitcnt lgkmcnt(4)
	v_mfma_f32_32x32x16_bf16 v[48:63], v[228:231], v[236:239], v[48:63]
	v_mfma_f32_32x32x16_bf16 v[32:47], v[228:231], v[240:243], v[32:47]
	ds_read_b128 v[228:231], v165 offset:4096
	s_waitcnt lgkmcnt(4)
	v_mfma_f32_32x32x16_bf16 v[16:31], v[232:235], v[236:239], v[16:31]
	v_mfma_f32_32x32x16_bf16 v[0:15], v[232:235], v[240:243], v[0:15]
	ds_read_b128 v[232:235], v165 offset:8192
	s_waitcnt lgkmcnt(2)
	v_mfma_f32_32x32x16_bf16 v[80:95], v[224:227], v[244:247], v[80:95]
	v_mfma_f32_32x32x16_bf16 v[64:79], v[224:227], v[248:251], v[64:79]
	s_waitcnt lgkmcnt(0)
	s_waitcnt vmcnt(0)
	s_barrier
	ds_read_b128 v[236:239], v170
	ds_read_b128 v[240:243], v170 offset:4096
	ds_read_b128 v[224:227], v162 offset:24576
	v_mfma_f32_32x32x16_bf16 v[48:63], v[228:231], v[244:247], v[48:63]
	v_mfma_f32_32x32x16_bf16 v[32:47], v[228:231], v[248:251], v[32:47]
	ds_read_b128 v[228:231], v162 offset:28672
	v_mfma_f32_32x32x16_bf16 v[16:31], v[232:235], v[244:247], v[16:31]
	v_mfma_f32_32x32x16_bf16 v[0:15], v[232:235], v[248:251], v[0:15]
	s_cmp_eq_u32 s101, 14
	s_cbranch_scc1 .Lgw_last
; template <int EPI, int MI>
; DI void gemm_tile(const GemmDesc& g, int tm, int tn, char* smem) {
;     ...
;   const int rowA = wm * (32 * MI) + r, rowB = wn * 64 + r;
;   const int hk = hh ^ ((r & 7) ^ ((r >> 3) & 3));
;     ...
;   G_GLDS(0, 0);
;   asm volatile("s_waitcnt vmcnt(0)" ::: "memory");
;   __syncthreads();
;   for (int kt = 0; kt < nk; kt += 2) {
;     if (kt + 1 < nk) G_GLDS(kt + 1, 1);
;     G_COMPUTE(0);
;     asm volatile("s_waitcnt vmcnt(0)" ::: "memory");
;     __syncthreads();
;     if (kt + 1 < nk) {
;       if (kt + 2 < nk) G_GLDS(kt + 2, 0);
;       G_COMPUTE(1);
;       asm volatile("s_waitcnt vmcnt(0)" ::: "memory");
;       __syncthreads();
;     }
;   }
	ds_read_b128 v[232:235], v162 offset:32768
	s_waitcnt lgkmcnt(2)
	v_mfma_f32_32x32x16_bf16 v[80:95], v[224:227], v[236:239], v[80:95]
	v_mfma_f32_32x32x16_bf16 v[64:79], v[224:227], v[240:243], v[64:79]
	s_mov_b32 m0, s100
	v_lshl_add_u64 v[106:107], v[252:253], 0, s[96:97]
	global_load_lds_dwordx4 v[106:107], off
	s_add_u32 m0, s100, 0x1000
	v_lshl_add_u64 v[106:107], v[252:253], 0, s[50:51]
	global_load_lds_dwordx4 v[106:107], off
	ds_read_b128 v[244:247], v171
	ds_read_b128 v[248:251], v171 offset:4096
	ds_read_b128 v[224:227], v163 offset:24576
	s_waitcnt lgkmcnt(4)
	v_mfma_f32_32x32x16_bf16 v[48:63], v[228:231], v[236:239], v[48:63]
	v_mfma_f32_32x32x16_bf16 v[32:47], v[228:231], v[240:243], v[32:47]
	s_add_u32 m0, s100, 0x2000
	v_lshl_add_u64 v[106:107], v[252:253], 0, s[24:25]
	global_load_lds_dwordx4 v[106:107], off
	s_add_u32 m0, s100, 0x3000
	v_lshl_add_u64 v[106:107], v[252:253], 0, s[26:27]
	global_load_lds_dwordx4 v[106:107], off
	ds_read_b128 v[228:231], v163 offset:28672
	s_waitcnt lgkmcnt(4)
	v_mfma_f32_32x32x16_bf16 v[16:31], v[232:235], v[236:239], v[16:31]
	v_mfma_f32_32x32x16_bf16 v[0:15], v[232:235], v[240:243], v[0:15]
	s_add_u32 m0, s100, 0x4000
	v_lshl_add_u64 v[106:107], v[252:253], 0, s[28:29]
	global_load_lds_dwordx4 v[106:107], off
	s_add_u32 m0, s100, 0x5000
	v_lshl_add_u64 v[106:107], v[252:253], 0, s[30:31]
	global_load_lds_dwordx4 v[106:107], off
	v_lshl_add_u64 v[252:253], v[252:253], 0, s[0:1]
	ds_read_b128 v[232:235], v163 offset:32768
	s_waitcnt lgkmcnt(2)
	v_mfma_f32_32x32x16_bf16 v[80:95], v[224:227], v[244:247], v[80:95]
	v_mfma_f32_32x32x16_bf16 v[64:79], v[224:227], v[248:251], v[64:79]
	s_mov_b64 s[16:17], 0x2100080
	s_add_u32 m0, s100, 0xc000
	v_lshl_add_u64 v[106:107], v[254:255], 0, s[16:17]
	global_load_lds_dwordx4 v[106:107], off
	s_mov_b64 s[16:17], 0x2110080
	s_add_u32 m0, s100, 0xd000
	v_lshl_add_u64 v[106:107], v[254:255], 0, s[16:17]
	global_load_lds_dwordx4 v[106:107], off
	ds_read_b128 v[236:239], v172
	ds_read_b128 v[240:243], v172 offset:4096
	ds_read_b128 v[224:227], v164 offset:24576
	s_waitcnt lgkmcnt(4)
	v_mfma_f32_32x32x16_bf16 v[48:63], v[228:231], v[244:247], v[48:63]
	v_mfma_f32_32x32x16_bf16 v[32:47], v[228:231], v[248:251], v[32:47]
	s_mov_b64 s[16:17], 0x2120080
	s_add_u32 m0, s100, 0xe000
	v_lshl_add_u64 v[106:107], v[254:255], 0, s[16:17]
	global_load_lds_dwordx4 v[106:107], off
	s_mov_b64 s[16:17], 0x2130080
	s_add_u32 m0, s100, 0xf000
	v_lshl_add_u64 v[106:107], v[254:255], 0, s[16:17]
	global_load_lds_dwordx4 v[106:107], off
	v_lshl_add_u64 v[254:255], v[254:255], 0, s[0:1]
	ds_read_b128 v[228:231], v164 offset:28672
	s_waitcnt lgkmcnt(4)
	v_mfma_f32_32x32x16_bf16 v[16:31], v[232:235], v[244:247], v[16:31]
	v_mfma_f32_32x32x16_bf16 v[0:15], v[232:235], v[248:251], v[0:15]
	ds_read_b128 v[232:235], v164 offset:32768
	s_waitcnt lgkmcnt(2)
	v_mfma_f32_32x32x16_bf16 v[80:95], v[224:227], v[236:239], v[80:95]
	v_mfma_f32_32x32x16_bf16 v[64:79], v[224:227], v[240:243], v[64:79]
	ds_read_b128 v[244:247], v173
	ds_read_b128 v[248:251], v173 offset:4096
	ds_read_b128 v[224:227], v165 offset:24576
	s_waitcnt lgkmcnt(4)
	v_mfma_f32_32x32x16_bf16 v[48:63], v[228:231], v[236:239], v[48:63]
	v_mfma_f32_32x32x16_bf16 v[32:47], v[228:231], v[240:243], v[32:47]
	ds_read_b128 v[228:231], v165 offset:28672
	s_waitcnt lgkmcnt(4)
	v_mfma_f32_32x32x16_bf16 v[16:31], v[232:235], v[236:239], v[16:31]
	v_mfma_f32_32x32x16_bf16 v[0:15], v[232:235], v[240:243], v[0:15]
	ds_read_b128 v[232:235], v165 offset:32768
	s_waitcnt lgkmcnt(2)
	v_mfma_f32_32x32x16_bf16 v[80:95], v[224:227], v[244:247], v[80:95]
	v_mfma_f32_32x32x16_bf16 v[64:79], v[224:227], v[248:251], v[64:79]
	s_waitcnt lgkmcnt(0)
	s_waitcnt vmcnt(0)
	s_barrier
	ds_read_b128 v[236:239], v166 offset:49152
	ds_read_b128 v[240:243], v166 offset:53248
	ds_read_b128 v[224:227], v162
	v_mfma_f32_32x32x16_bf16 v[48:63], v[228:231], v[244:247], v[48:63]
	v_mfma_f32_32x32x16_bf16 v[32:47], v[228:231], v[248:251], v[32:47]
	ds_read_b128 v[228:231], v162 offset:4096
	v_mfma_f32_32x32x16_bf16 v[16:31], v[232:235], v[244:247], v[16:31]
	v_mfma_f32_32x32x16_bf16 v[0:15], v[232:235], v[248:251], v[0:15]
	s_add_u32 s101, s101, 2
	s_branch .Lgw_loop

; template <int EPI, int MI>
; DI void gemm_tile(const GemmDesc& g, int tm, int tn, char* smem) {
;     ...
;   const int rowA = wm * (32 * MI) + r, rowB = wn * 64 + r;
;   const int hk = hh ^ ((r & 7) ^ ((r >> 3) & 3));
;     ...
;   G_GLDS(0, 0);
;   asm volatile("s_waitcnt vmcnt(0)" ::: "memory");
;   __syncthreads();
;   for (int kt = 0; kt < nk; kt += 2) {
;     if (kt + 1 < nk) G_GLDS(kt + 1, 1);
;     G_COMPUTE(0);
;     asm volatile("s_waitcnt vmcnt(0)" ::: "memory");
;     __syncthreads();
;     if (kt + 1 < nk) {
;       if (kt + 2 < nk) G_GLDS(kt + 2, 0);
;       G_COMPUTE(1);
;       asm volatile("s_waitcnt vmcnt(0)" ::: "memory");
;       __syncthreads();
;     }
;   }
.Lgc_loop:
	ds_read_b128 v[248:251], v103 offset:32768
	ds_read_b128 v[252:255], v103 offset:36864
	ds_read_b128 v[232:235], v99
	s_waitcnt lgkmcnt(4)
	v_mfma_f32_32x32x16_bf16 v[48:63], v[224:227], v[240:243], v[48:63]
	v_mfma_f32_32x32x16_bf16 v[32:47], v[224:227], v[244:247], v[32:47]
	s_add_u32 m0, s100, 0x4000
	v_lshl_add_u64 v[106:107], v[72:73], 0, s[96:97]
	global_load_lds_dwordx4 v[106:107], off
	s_add_u32 m0, s100, 0x5000
	v_lshl_add_u64 v[106:107], v[72:73], 0, s[50:51]
	global_load_lds_dwordx4 v[106:107], off
	ds_read_b128 v[236:239], v99 offset:4096
	s_waitcnt lgkmcnt(4)
	v_mfma_f32_32x32x16_bf16 v[16:31], v[228:231], v[240:243], v[16:31]
	v_mfma_f32_32x32x16_bf16 v[0:15], v[228:231], v[244:247], v[0:15]
	s_add_u32 m0, s100, 0x6000
	v_lshl_add_u64 v[106:107], v[72:73], 0, s[24:25]
	global_load_lds_dwordx4 v[106:107], off
	s_add_u32 m0, s100, 0x7000
	v_lshl_add_u64 v[106:107], v[72:73], 0, s[26:27]
	global_load_lds_dwordx4 v[106:107], off
	v_lshl_add_u64 v[72:73], v[72:73], 0, s[44:45]
	ds_read_b128 v[240:243], v104 offset:32768
	ds_read_b128 v[244:247], v104 offset:36864
	ds_read_b128 v[224:227], v100
	s_waitcnt lgkmcnt(4)
	v_mfma_f32_32x32x16_bf16 v[48:63], v[232:235], v[248:251], v[48:63]
	v_mfma_f32_32x32x16_bf16 v[32:47], v[232:235], v[252:255], v[32:47]
	s_mov_b64 s[0:1], 0xb00080
	s_add_u32 m0, s100, 0xc000
	v_lshl_add_u64 v[106:107], v[74:75], 0, s[0:1]
	global_load_lds_dwordx4 v[106:107], off
	s_mov_b64 s[0:1], 0xb10080
	s_add_u32 m0, s100, 0xd000
	v_lshl_add_u64 v[106:107], v[74:75], 0, s[0:1]
	global_load_lds_dwordx4 v[106:107], off
	ds_read_b128 v[228:231], v100 offset:4096
	s_waitcnt lgkmcnt(4)
	v_mfma_f32_32x32x16_bf16 v[16:31], v[236:239], v[248:251], v[16:31]
	v_mfma_f32_32x32x16_bf16 v[0:15], v[236:239], v[252:255], v[0:15]
	s_mov_b64 s[0:1], 0xb20080
	s_add_u32 m0, s100, 0xe000
	v_lshl_add_u64 v[106:107], v[74:75], 0, s[0:1]
	global_load_lds_dwordx4 v[106:107], off
	s_mov_b64 s[0:1], 0xb30080
	s_add_u32 m0, s100, 0xf000
	v_lshl_add_u64 v[106:107], v[74:75], 0, s[0:1]
	global_load_lds_dwordx4 v[106:107], off
	v_lshl_add_u64 v[74:75], v[74:75], 0, s[44:45]
	ds_read_b128 v[248:251], v105 offset:32768
	ds_read_b128 v[252:255], v105 offset:36864
	ds_read_b128 v[232:235], v101
	s_waitcnt lgkmcnt(4)
	v_mfma_f32_32x32x16_bf16 v[48:63], v[224:227], v[240:243], v[48:63]
	v_mfma_f32_32x32x16_bf16 v[32:47], v[224:227], v[244:247], v[32:47]
	ds_read_b128 v[236:239], v101 offset:4096
	s_waitcnt lgkmcnt(4)
	v_mfma_f32_32x32x16_bf16 v[16:31], v[228:231], v[240:243], v[16:31]
	v_mfma_f32_32x32x16_bf16 v[0:15], v[228:231], v[244:247], v[0:15]
	s_waitcnt lgkmcnt(0)
	s_waitcnt vmcnt(0)
	s_barrier
	ds_read_b128 v[240:243], v102 offset:49152
	ds_read_b128 v[244:247], v102 offset:53248
	ds_read_b128 v[224:227], v98 offset:16384
	v_mfma_f32_32x32x16_bf16 v[48:63], v[232:235], v[248:251], v[48:63]
	v_mfma_f32_32x32x16_bf16 v[32:47], v[232:235], v[252:255], v[32:47]
	ds_read_b128 v[228:231], v98 offset:20480
	v_mfma_f32_32x32x16_bf16 v[16:31], v[236:239], v[248:251], v[16:31]
	v_mfma_f32_32x32x16_bf16 v[0:15], v[236:239], v[252:255], v[0:15]
	s_cmp_eq_u32 s101, 14
	s_cbranch_scc1 .Lgc_last
	ds_read_b128 v[248:251], v103 offset:49152
	ds_read_b128 v[252:255], v103 offset:53248
	ds_read_b128 v[232:235], v99 offset:16384
	s_waitcnt lgkmcnt(4)
	v_mfma_f32_32x32x16_bf16 v[48:63], v[224:227], v[240:243], v[48:63]
	v_mfma_f32_32x32x16_bf16 v[32:47], v[224:227], v[244:247], v[32:47]
	s_mov_b32 m0, s100
	v_lshl_add_u64 v[106:107], v[72:73], 0, s[96:97]
	global_load_lds_dwordx4 v[106:107], off
	s_add_u32 m0, s100, 0x1000
	v_lshl_add_u64 v[106:107], v[72:73], 0, s[50:51]
	global_load_lds_dwordx4 v[106:107], off
	ds_read_b128 v[236:239], v99 offset:20480
	s_waitcnt lgkmcnt(4)
	v_mfma_f32_32x32x16_bf16 v[16:31], v[228:231], v[240:243], v[16:31]
	v_mfma_f32_32x32x16_bf16 v[0:15], v[228:231], v[244:247], v[0:15]
	s_add_u32 m0, s100, 0x2000
	v_lshl_add_u64 v[106:107], v[72:73], 0, s[24:25]
	global_load_lds_dwordx4 v[106:107], off
	s_add_u32 m0, s100, 0x3000
	v_lshl_add_u64 v[106:107], v[72:73], 0, s[26:27]
	global_load_lds_dwordx4 v[106:107], off
	v_lshl_add_u64 v[72:73], v[72:73], 0, s[44:45]
	ds_read_b128 v[240:243], v104 offset:49152
	ds_read_b128 v[244:247], v104 offset:53248
	ds_read_b128 v[224:227], v100 offset:16384
	s_waitcnt lgkmcnt(4)
	v_mfma_f32_32x32x16_bf16 v[48:63], v[232:235], v[248:251], v[48:63]
	v_mfma_f32_32x32x16_bf16 v[32:47], v[232:235], v[252:255], v[32:47]
	s_mov_b64 s[0:1], 0xb00080
	s_add_u32 m0, s100, 0x8000
	v_lshl_add_u64 v[106:107], v[74:75], 0, s[0:1]
	global_load_lds_dwordx4 v[106:107], off
	s_mov_b64 s[0:1], 0xb10080
	s_add_u32 m0, s100, 0x9000
	v_lshl_add_u64 v[106:107], v[74:75], 0, s[0:1]
	global_load_lds_dwordx4 v[106:107], off
	ds_read_b128 v[228:231], v100 offset:20480
	s_waitcnt lgkmcnt(4)
	v_mfma_f32_32x32x16_bf16 v[16:31], v[236:239], v[248:251], v[16:31]
	v_mfma_f32_32x32x16_bf16 v[0:15], v[236:239], v[252:255], v[0:15]
	s_mov_b64 s[0:1], 0xb20080
	s_add_u32 m0, s100, 0xa000
	v_lshl_add_u64 v[106:107], v[74:75], 0, s[0:1]
	global_load_lds_dwordx4 v[106:107], off
	s_mov_b64 s[0:1], 0xb30080
	s_add_u32 m0, s100, 0xb000
	v_lshl_add_u64 v[106:107], v[74:75], 0, s[0:1]
	global_load_lds_dwordx4 v[106:107], off
	v_lshl_add_u64 v[74:75], v[74:75], 0, s[44:45]
	ds_read_b128 v[248:251], v105 offset:49152
	ds_read_b128 v[252:255], v105 offset:53248
	ds_read_b128 v[232:235], v101 offset:16384
	s_waitcnt lgkmcnt(4)
	v_mfma_f32_32x32x16_bf16 v[48:63], v[224:227], v[240:243], v[48:63]
	v_mfma_f32_32x32x16_bf16 v[32:47], v[224:227], v[244:247], v[32:47]
	ds_read_b128 v[236:239], v101 offset:20480
	s_waitcnt lgkmcnt(4)
	v_mfma_f32_32x32x16_bf16 v[16:31], v[228:231], v[240:243], v[16:31]
	v_mfma_f32_32x32x16_bf16 v[0:15], v[228:231], v[244:247], v[0:15]
	s_waitcnt lgkmcnt(0)
	s_waitcnt vmcnt(0)
	s_barrier
	ds_read_b128 v[240:243], v102 offset:32768
	ds_read_b128 v[244:247], v102 offset:36864
	ds_read_b128 v[224:227], v98
	v_mfma_f32_32x32x16_bf16 v[48:63], v[232:235], v[248:251], v[48:63]
	v_mfma_f32_32x32x16_bf16 v[32:47], v[232:235], v[252:255], v[32:47]
	ds_read_b128 v[228:231], v98 offset:4096
	v_mfma_f32_32x32x16_bf16 v[16:31], v[236:239], v[248:251], v[16:31]
	v_mfma_f32_32x32x16_bf16 v[0:15], v[236:239], v[252:255], v[0:15]
	s_add_u32 s101, s101, 2
	s_branch .Lgc_loop

; template <int EPI, int MI>
; DI void gemm_tile(const GemmDesc& g, int tm, int tn, char* smem) {
;     ...
;   const int rowA = wm * (32 * MI) + r, rowB = wn * 64 + r;
;   const int hk = hh ^ ((r & 7) ^ ((r >> 3) & 3));
;     ...
;   G_GLDS(0, 0);
;   asm volatile("s_waitcnt vmcnt(0)" ::: "memory");
;   __syncthreads();
;   for (int kt = 0; kt < nk; kt += 2) {
;     if (kt + 1 < nk) G_GLDS(kt + 1, 1);
;     G_COMPUTE(0);
;     asm volatile("s_waitcnt vmcnt(0)" ::: "memory");
;     __syncthreads();
;     if (kt + 1 < nk) {
;       if (kt + 2 < nk) G_GLDS(kt + 2, 0);
;       G_COMPUTE(1);
;       asm volatile("s_waitcnt vmcnt(0)" ::: "memory");
;       __syncthreads();
;     }
;   }
.Lgb_loop:
	ds_read_b128 v[232:235], v162 offset:8192
	s_waitcnt lgkmcnt(2)
	v_mfma_f32_32x32x16_bf16 v[80:95], v[224:227], v[236:239], v[80:95]
	v_mfma_f32_32x32x16_bf16 v[64:79], v[224:227], v[240:243], v[64:79]
	s_add_u32 m0, s100, 0x6000
	v_lshl_add_u64 v[106:107], v[252:253], 0, s[96:97]
	global_load_lds_dwordx4 v[106:107], off
	s_add_u32 m0, s100, 0x7000
	v_lshl_add_u64 v[106:107], v[252:253], 0, s[50:51]
	global_load_lds_dwordx4 v[106:107], off
	ds_read_b128 v[244:247], v167 offset:49152
	ds_read_b128 v[248:251], v167 offset:53248
	ds_read_b128 v[224:227], v163
	s_waitcnt lgkmcnt(4)
	v_mfma_f32_32x32x16_bf16 v[48:63], v[228:231], v[236:239], v[48:63]
	v_mfma_f32_32x32x16_bf16 v[32:47], v[228:231], v[240:243], v[32:47]
	s_add_u32 m0, s100, 0x8000
	v_lshl_add_u64 v[106:107], v[252:253], 0, s[24:25]
	global_load_lds_dwordx4 v[106:107], off
	s_add_u32 m0, s100, 0x9000
	v_lshl_add_u64 v[106:107], v[252:253], 0, s[26:27]
	global_load_lds_dwordx4 v[106:107], off
	ds_read_b128 v[228:231], v163 offset:4096
	s_waitcnt lgkmcnt(4)
	v_mfma_f32_32x32x16_bf16 v[16:31], v[232:235], v[236:239], v[16:31]
	v_mfma_f32_32x32x16_bf16 v[0:15], v[232:235], v[240:243], v[0:15]
	s_add_u32 m0, s100, 0xa000
	v_lshl_add_u64 v[106:107], v[252:253], 0, s[28:29]
	global_load_lds_dwordx4 v[106:107], off
	s_add_u32 m0, s100, 0xb000
	v_lshl_add_u64 v[106:107], v[252:253], 0, s[30:31]
	global_load_lds_dwordx4 v[106:107], off
	v_lshl_add_u64 v[252:253], v[252:253], 0, s[0:1]
	ds_read_b128 v[232:235], v163 offset:8192
	s_waitcnt lgkmcnt(2)
	v_mfma_f32_32x32x16_bf16 v[80:95], v[224:227], v[244:247], v[80:95]
	v_mfma_f32_32x32x16_bf16 v[64:79], v[224:227], v[248:251], v[64:79]
	s_mov_b64 s[16:17], 0xb00080
	s_add_u32 m0, s100, 0x10000
	v_lshl_add_u64 v[106:107], v[254:255], 0, s[16:17]
	global_load_lds_dwordx4 v[106:107], off
	s_mov_b64 s[16:17], 0xb10080
	s_add_u32 m0, s100, 0x11000
	v_lshl_add_u64 v[106:107], v[254:255], 0, s[16:17]
	global_load_lds_dwordx4 v[106:107], off
	ds_read_b128 v[236:239], v168 offset:49152
	ds_read_b128 v[240:243], v168 offset:53248
	ds_read_b128 v[224:227], v164
	s_waitcnt lgkmcnt(4)
	v_mfma_f32_32x32x16_bf16 v[48:63], v[228:231], v[244:247], v[48:63]
	v_mfma_f32_32x32x16_bf16 v[32:47], v[228:231], v[248:251], v[32:47]
	s_mov_b64 s[16:17], 0xb20080
	s_add_u32 m0, s100, 0x12000
	v_lshl_add_u64 v[106:107], v[254:255], 0, s[16:17]
	global_load_lds_dwordx4 v[106:107], off
	s_mov_b64 s[16:17], 0xb30080
	s_add_u32 m0, s100, 0x13000
	v_lshl_add_u64 v[106:107], v[254:255], 0, s[16:17]
	global_load_lds_dwordx4 v[106:107], off
	v_lshl_add_u64 v[254:255], v[254:255], 0, s[0:1]
	ds_read_b128 v[228:231], v164 offset:4096
	s_waitcnt lgkmcnt(4)
	v_mfma_f32_32x32x16_bf16 v[16:31], v[232:235], v[244:247], v[16:31]
	v_mfma_f32_32x32x16_bf16 v[0:15], v[232:235], v[248:251], v[0:15]
	ds_read_b128 v[232:235], v164 offset:8192
	s_waitcnt lgkmcnt(2)
	v_mfma_f32_32x32x16_bf16 v[80:95], v[224:227], v[236:239], v[80:95]
	v_mfma_f32_32x32x16_bf16 v[64:79], v[224:227], v[240:243], v[64:79]
	ds_read_b128 v[244:247], v169 offset:49152
	ds_read_b128 v[248:251], v169 offset:53248
	ds_read_b128 v[224:227], v165
	s_waitcnt lgkmcnt(4)
	v_mfma_f32_32x32x16_bf16 v[48:63], v[228:231], v[236:239], v[48:63]
	v_mfma_f32_32x32x16_bf16 v[32:47], v[228:231], v[240:243], v[32:47]
	ds_read_b128 v[228:231], v165 offset:4096
	s_waitcnt lgkmcnt(4)
	v_mfma_f32_32x32x16_bf16 v[16:31], v[232:235], v[236:239], v[16:31]
	v_mfma_f32_32x32x16_bf16 v[0:15], v[232:235], v[240:243], v[0:15]
	ds_read_b128 v[232:235], v165 offset:8192
	s_waitcnt lgkmcnt(2)
	v_mfma_f32_32x32x16_bf16 v[80:95], v[224:227], v[244:247], v[80:95]
	v_mfma_f32_32x32x16_bf16 v[64:79], v[224:227], v[248:251], v[64:79]
	s_waitcnt lgkmcnt(0)
	s_waitcnt vmcnt(0)
	s_barrier
	ds_read_b128 v[236:239], v170
	ds_read_b128 v[240:243], v170 offset:4096
	ds_read_b128 v[224:227], v162 offset:24576
	v_mfma_f32_32x32x16_bf16 v[48:63], v[228:231], v[244:247], v[48:63]
	v_mfma_f32_32x32x16_bf16 v[32:47], v[228:231], v[248:251], v[32:47]
	ds_read_b128 v[228:231], v162 offset:28672
	v_mfma_f32_32x32x16_bf16 v[16:31], v[232:235], v[244:247], v[16:31]
	v_mfma_f32_32x32x16_bf16 v[0:15], v[232:235], v[248:251], v[0:15]
	s_cmp_eq_u32 s101, 14
	s_cbranch_scc1 .Lgb_last
; template <int EPI, int MI>
; DI void gemm_tile(const GemmDesc& g, int tm, int tn, char* smem) {
;     ...
;   const int rowA = wm * (32 * MI) + r, rowB = wn * 64 + r;
;   const int hk = hh ^ ((r & 7) ^ ((r >> 3) & 3));
;     ...
;   G_GLDS(0, 0);
;   asm volatile("s_waitcnt vmcnt(0)" ::: "memory");
;   __syncthreads();
;   for (int kt = 0; kt < nk; kt += 2) {
;     if (kt + 1 < nk) G_GLDS(kt + 1, 1);
;     G_COMPUTE(0);
;     asm volatile("s_waitcnt vmcnt(0)" ::: "memory");
;     __syncthreads();
;     if (kt + 1 < nk) {
;       if (kt + 2 < nk) G_GLDS(kt + 2, 0);
;       G_COMPUTE(1);
;       asm volatile("s_waitcnt vmcnt(0)" ::: "memory");
;       __syncthreads();
;     }
;   }
	ds_read_b128 v[232:235], v162 offset:32768
	s_waitcnt lgkmcnt(2)
	v_mfma_f32_32x32x16_bf16 v[80:95], v[224:227], v[236:239], v[80:95]
	v_mfma_f32_32x32x16_bf16 v[64:79], v[224:227], v[240:243], v[64:79]
	s_mov_b32 m0, s100
	v_lshl_add_u64 v[106:107], v[252:253], 0, s[96:97]
	global_load_lds_dwordx4 v[106:107], off
	s_add_u32 m0, s100, 0x1000
	v_lshl_add_u64 v[106:107], v[252:253], 0, s[50:51]
	global_load_lds_dwordx4 v[106:107], off
	ds_read_b128 v[244:247], v171
	ds_read_b128 v[248:251], v171 offset:4096
	ds_read_b128 v[224:227], v163 offset:24576
	s_waitcnt lgkmcnt(4)
	v_mfma_f32_32x32x16_bf16 v[48:63], v[228:231], v[236:239], v[48:63]
	v_mfma_f32_32x32x16_bf16 v[32:47], v[228:231], v[240:243], v[32:47]
	s_add_u32 m0, s100, 0x2000
	v_lshl_add_u64 v[106:107], v[252:253], 0, s[24:25]
	global_load_lds_dwordx4 v[106:107], off
	s_add_u32 m0, s100, 0x3000
	v_lshl_add_u64 v[106:107], v[252:253], 0, s[26:27]
	global_load_lds_dwordx4 v[106:107], off
	ds_read_b128 v[228:231], v163 offset:28672
	s_waitcnt lgkmcnt(4)
	v_mfma_f32_32x32x16_bf16 v[16:31], v[232:235], v[236:239], v[16:31]
	v_mfma_f32_32x32x16_bf16 v[0:15], v[232:235], v[240:243], v[0:15]
	s_add_u32 m0, s100, 0x4000
	v_lshl_add_u64 v[106:107], v[252:253], 0, s[28:29]
	global_load_lds_dwordx4 v[106:107], off
	s_add_u32 m0, s100, 0x5000
	v_lshl_add_u64 v[106:107], v[252:253], 0, s[30:31]
	global_load_lds_dwordx4 v[106:107], off
	v_lshl_add_u64 v[252:253], v[252:253], 0, s[0:1]
	ds_read_b128 v[232:235], v163 offset:32768
	s_waitcnt lgkmcnt(2)
	v_mfma_f32_32x32x16_bf16 v[80:95], v[224:227], v[244:247], v[80:95]
	v_mfma_f32_32x32x16_bf16 v[64:79], v[224:227], v[248:251], v[64:79]
	s_mov_b64 s[16:17], 0xb00080
	s_add_u32 m0, s100, 0xc000
	v_lshl_add_u64 v[106:107], v[254:255], 0, s[16:17]
	global_load_lds_dwordx4 v[106:107], off
	s_mov_b64 s[16:17], 0xb10080
	s_add_u32 m0, s100, 0xd000
	v_lshl_add_u64 v[106:107], v[254:255], 0, s[16:17]
	global_load_lds_dwordx4 v[106:107], off
	ds_read_b128 v[236:239], v172
	ds_read_b128 v[240:243], v172 offset:4096
	ds_read_b128 v[224:227], v164 offset:24576
	s_waitcnt lgkmcnt(4)
	v_mfma_f32_32x32x16_bf16 v[48:63], v[228:231], v[244:247], v[48:63]
	v_mfma_f32_32x32x16_bf16 v[32:47], v[228:231], v[248:251], v[32:47]
	s_mov_b64 s[16:17], 0xb20080
	s_add_u32 m0, s100, 0xe000
	v_lshl_add_u64 v[106:107], v[254:255], 0, s[16:17]
	global_load_lds_dwordx4 v[106:107], off
	s_mov_b64 s[16:17], 0xb30080
	s_add_u32 m0, s100, 0xf000
	v_lshl_add_u64 v[106:107], v[254:255], 0, s[16:17]
	global_load_lds_dwordx4 v[106:107], off
	v_lshl_add_u64 v[254:255], v[254:255], 0, s[0:1]
	ds_read_b128 v[228:231], v164 offset:28672
	s_waitcnt lgkmcnt(4)
	v_mfma_f32_32x32x16_bf16 v[16:31], v[232:235], v[244:247], v[16:31]
	v_mfma_f32_32x32x16_bf16 v[0:15], v[232:235], v[248:251], v[0:15]
	ds_read_b128 v[232:235], v164 offset:32768
	s_waitcnt lgkmcnt(2)
	v_mfma_f32_32x32x16_bf16 v[80:95], v[224:227], v[236:239], v[80:95]
	v_mfma_f32_32x32x16_bf16 v[64:79], v[224:227], v[240:243], v[64:79]
	ds_read_b128 v[244:247], v173
	ds_read_b128 v[248:251], v173 offset:4096
	ds_read_b128 v[224:227], v165 offset:24576
	s_waitcnt lgkmcnt(4)
	v_mfma_f32_32x32x16_bf16 v[48:63], v[228:231], v[236:239], v[48:63]
	v_mfma_f32_32x32x16_bf16 v[32:47], v[228:231], v[240:243], v[32:47]
	ds_read_b128 v[228:231], v165 offset:28672
	s_waitcnt lgkmcnt(4)
	v_mfma_f32_32x32x16_bf16 v[16:31], v[232:235], v[236:239], v[16:31]
	v_mfma_f32_32x32x16_bf16 v[0:15], v[232:235], v[240:243], v[0:15]
	ds_read_b128 v[232:235], v165 offset:32768
	s_waitcnt lgkmcnt(2)
	v_mfma_f32_32x32x16_bf16 v[80:95], v[224:227], v[244:247], v[80:95]
	v_mfma_f32_32x32x16_bf16 v[64:79], v[224:227], v[248:251], v[64:79]
	s_waitcnt lgkmcnt(0)
	s_waitcnt vmcnt(0)
	s_barrier
	ds_read_b128 v[236:239], v166 offset:49152
	ds_read_b128 v[240:243], v166 offset:53248
	ds_read_b128 v[224:227], v162
	v_mfma_f32_32x32x16_bf16 v[48:63], v[228:231], v[244:247], v[48:63]
	v_mfma_f32_32x32x16_bf16 v[32:47], v[228:231], v[248:251], v[32:47]
	ds_read_b128 v[228:231], v162 offset:4096
	v_mfma_f32_32x32x16_bf16 v[16:31], v[232:235], v[244:247], v[16:31]
	v_mfma_f32_32x32x16_bf16 v[0:15], v[232:235], v[248:251], v[0:15]
	s_add_u32 s101, s101, 2
	s_branch .Lgb_loop

; template <int EPI, int MI>
; DI void gemm_tile(const GemmDesc& g, int tm, int tn, char* smem) {
;     ...
;   const int rowA = wm * (32 * MI) + r, rowB = wn * 64 + r;
;   const int hk = hh ^ ((r & 7) ^ ((r >> 3) & 3));
;     ...
;   G_GLDS(0, 0);
;   asm volatile("s_waitcnt vmcnt(0)" ::: "memory");
;   __syncthreads();
;   for (int kt = 0; kt < nk; kt += 2) {
;     if (kt + 1 < nk) G_GLDS(kt + 1, 1);
;     G_COMPUTE(0);
;     asm volatile("s_waitcnt vmcnt(0)" ::: "memory");
;     __syncthreads();
;     if (kt + 1 < nk) {
;       if (kt + 2 < nk) G_GLDS(kt + 2, 0);
;       G_COMPUTE(1);
;       asm volatile("s_waitcnt vmcnt(0)" ::: "memory");
;       __syncthreads();
;     }
;   }
.Lgf_loop:
	ds_read_b128 v[248:251], v98 offset:32768
	ds_read_b128 v[252:255], v98 offset:36864
	ds_read_b128 v[232:235], v93
	s_waitcnt lgkmcnt(4)
	v_mfma_f32_32x32x16_bf16 v[48:63], v[224:227], v[240:243], v[48:63]
	v_mfma_f32_32x32x16_bf16 v[32:47], v[224:227], v[244:247], v[32:47]
	s_mov_b64 s[4:5], 0x5872080
	s_add_u32 m0, s100, 0x4000
	v_lshl_add_u64 v[102:103], v[104:105], 0, s[4:5]
	global_load_lds_dwordx4 v[102:103], off
	s_mov_b64 s[4:5], 0x589e080
	s_add_u32 m0, s100, 0x5000
	v_lshl_add_u64 v[102:103], v[104:105], 0, s[4:5]
	global_load_lds_dwordx4 v[102:103], off
	ds_read_b128 v[236:239], v93 offset:4096
	s_waitcnt lgkmcnt(4)
	v_mfma_f32_32x32x16_bf16 v[16:31], v[228:231], v[240:243], v[16:31]
	v_mfma_f32_32x32x16_bf16 v[0:15], v[228:231], v[244:247], v[0:15]
	s_mov_b64 s[4:5], 0x58ca080
	s_add_u32 m0, s100, 0x6000
	v_lshl_add_u64 v[102:103], v[104:105], 0, s[4:5]
	global_load_lds_dwordx4 v[102:103], off
	s_mov_b64 s[4:5], 0x58f6080
	s_add_u32 m0, s100, 0x7000
	v_lshl_add_u64 v[102:103], v[104:105], 0, s[4:5]
	global_load_lds_dwordx4 v[102:103], off
	v_lshl_add_u64 v[104:105], v[104:105], 0, s[46:47]
	ds_read_b128 v[240:243], v99 offset:32768
	ds_read_b128 v[244:247], v99 offset:36864
	ds_read_b128 v[224:227], v94
	s_waitcnt lgkmcnt(4)
	v_mfma_f32_32x32x16_bf16 v[48:63], v[232:235], v[248:251], v[48:63]
	v_mfma_f32_32x32x16_bf16 v[32:47], v[232:235], v[252:255], v[32:47]
	s_mov_b64 s[4:5], 0x1b80080
	s_add_u32 m0, s100, 0xc000
	v_lshl_add_u64 v[102:103], v[106:107], 0, s[4:5]
	global_load_lds_dwordx4 v[102:103], off
	s_mov_b64 s[4:5], 0x1bac080
	s_add_u32 m0, s100, 0xd000
	v_lshl_add_u64 v[102:103], v[106:107], 0, s[4:5]
	global_load_lds_dwordx4 v[102:103], off
	ds_read_b128 v[228:231], v94 offset:4096
	s_waitcnt lgkmcnt(4)
	v_mfma_f32_32x32x16_bf16 v[16:31], v[236:239], v[248:251], v[16:31]
	v_mfma_f32_32x32x16_bf16 v[0:15], v[236:239], v[252:255], v[0:15]
	s_mov_b64 s[4:5], 0x1bd8080
	s_add_u32 m0, s100, 0xe000
	v_lshl_add_u64 v[102:103], v[106:107], 0, s[4:5]
	global_load_lds_dwordx4 v[102:103], off
	s_mov_b64 s[4:5], 0x1c04080
	s_add_u32 m0, s100, 0xf000
	v_lshl_add_u64 v[102:103], v[106:107], 0, s[4:5]
	global_load_lds_dwordx4 v[102:103], off
	v_lshl_add_u64 v[106:107], v[106:107], 0, s[46:47]
	ds_read_b128 v[248:251], v100 offset:32768
	ds_read_b128 v[252:255], v100 offset:36864
	ds_read_b128 v[232:235], v95
	s_waitcnt lgkmcnt(4)
	v_mfma_f32_32x32x16_bf16 v[48:63], v[224:227], v[240:243], v[48:63]
	v_mfma_f32_32x32x16_bf16 v[32:47], v[224:227], v[244:247], v[32:47]
	ds_read_b128 v[236:239], v95 offset:4096
	s_waitcnt lgkmcnt(4)
	v_mfma_f32_32x32x16_bf16 v[16:31], v[228:231], v[240:243], v[16:31]
	v_mfma_f32_32x32x16_bf16 v[0:15], v[228:231], v[244:247], v[0:15]
	s_waitcnt lgkmcnt(0)
	s_waitcnt vmcnt(0)
	s_barrier
	ds_read_b128 v[240:243], v97 offset:49152
	ds_read_b128 v[244:247], v97 offset:53248
	ds_read_b128 v[224:227], v92 offset:16384
	v_mfma_f32_32x32x16_bf16 v[48:63], v[232:235], v[248:251], v[48:63]
	v_mfma_f32_32x32x16_bf16 v[32:47], v[232:235], v[252:255], v[32:47]
	ds_read_b128 v[228:231], v92 offset:20480
	v_mfma_f32_32x32x16_bf16 v[16:31], v[236:239], v[248:251], v[16:31]
	v_mfma_f32_32x32x16_bf16 v[0:15], v[236:239], v[252:255], v[0:15]
	s_cmp_eq_u32 s101, 42
	s_cbranch_scc1 .Lgf_last
	ds_read_b128 v[248:251], v98 offset:49152
	ds_read_b128 v[252:255], v98 offset:53248
	ds_read_b128 v[232:235], v93 offset:16384
	s_waitcnt lgkmcnt(4)
	v_mfma_f32_32x32x16_bf16 v[48:63], v[224:227], v[240:243], v[48:63]
	v_mfma_f32_32x32x16_bf16 v[32:47], v[224:227], v[244:247], v[32:47]
	s_mov_b64 s[4:5], 0x5872080
	s_mov_b32 m0, s100
	v_lshl_add_u64 v[102:103], v[104:105], 0, s[4:5]
	global_load_lds_dwordx4 v[102:103], off
	s_mov_b64 s[4:5], 0x589e080
	s_add_u32 m0, s100, 0x1000
	v_lshl_add_u64 v[102:103], v[104:105], 0, s[4:5]
	global_load_lds_dwordx4 v[102:103], off
	ds_read_b128 v[236:239], v93 offset:20480
	s_waitcnt lgkmcnt(4)
	v_mfma_f32_32x32x16_bf16 v[16:31], v[228:231], v[240:243], v[16:31]
	v_mfma_f32_32x32x16_bf16 v[0:15], v[228:231], v[244:247], v[0:15]
	s_mov_b64 s[4:5], 0x58ca080
	s_add_u32 m0, s100, 0x2000
	v_lshl_add_u64 v[102:103], v[104:105], 0, s[4:5]
	global_load_lds_dwordx4 v[102:103], off
	s_mov_b64 s[4:5], 0x58f6080
	s_add_u32 m0, s100, 0x3000
	v_lshl_add_u64 v[102:103], v[104:105], 0, s[4:5]
	global_load_lds_dwordx4 v[102:103], off
	v_lshl_add_u64 v[104:105], v[104:105], 0, s[46:47]
	ds_read_b128 v[240:243], v99 offset:49152
	ds_read_b128 v[244:247], v99 offset:53248
	ds_read_b128 v[224:227], v94 offset:16384
	s_waitcnt lgkmcnt(4)
	v_mfma_f32_32x32x16_bf16 v[48:63], v[232:235], v[248:251], v[48:63]
	v_mfma_f32_32x32x16_bf16 v[32:47], v[232:235], v[252:255], v[32:47]
	s_mov_b64 s[4:5], 0x1b80080
	s_add_u32 m0, s100, 0x8000
	v_lshl_add_u64 v[102:103], v[106:107], 0, s[4:5]
	global_load_lds_dwordx4 v[102:103], off
	s_mov_b64 s[4:5], 0x1bac080
	s_add_u32 m0, s100, 0x9000
	v_lshl_add_u64 v[102:103], v[106:107], 0, s[4:5]
	global_load_lds_dwordx4 v[102:103], off
	ds_read_b128 v[228:231], v94 offset:20480
	s_waitcnt lgkmcnt(4)
	v_mfma_f32_32x32x16_bf16 v[16:31], v[236:239], v[248:251], v[16:31]
	v_mfma_f32_32x32x16_bf16 v[0:15], v[236:239], v[252:255], v[0:15]
	s_mov_b64 s[4:5], 0x1bd8080
	s_add_u32 m0, s100, 0xa000
	v_lshl_add_u64 v[102:103], v[106:107], 0, s[4:5]
	global_load_lds_dwordx4 v[102:103], off
	s_mov_b64 s[4:5], 0x1c04080
	s_add_u32 m0, s100, 0xb000
	v_lshl_add_u64 v[102:103], v[106:107], 0, s[4:5]
	global_load_lds_dwordx4 v[102:103], off
	v_lshl_add_u64 v[106:107], v[106:107], 0, s[46:47]
	ds_read_b128 v[248:251], v100 offset:49152
	ds_read_b128 v[252:255], v100 offset:53248
	ds_read_b128 v[232:235], v95 offset:16384
	s_waitcnt lgkmcnt(4)
	v_mfma_f32_32x32x16_bf16 v[48:63], v[224:227], v[240:243], v[48:63]
	v_mfma_f32_32x32x16_bf16 v[32:47], v[224:227], v[244:247], v[32:47]
	ds_read_b128 v[236:239], v95 offset:20480
	s_waitcnt lgkmcnt(4)
	v_mfma_f32_32x32x16_bf16 v[16:31], v[228:231], v[240:243], v[16:31]
	v_mfma_f32_32x32x16_bf16 v[0:15], v[228:231], v[244:247], v[0:15]
	s_waitcnt lgkmcnt(0)
	s_waitcnt vmcnt(0)
	s_barrier
	ds_read_b128 v[240:243], v97 offset:32768
	ds_read_b128 v[244:247], v97 offset:36864
	ds_read_b128 v[224:227], v92
	v_mfma_f32_32x32x16_bf16 v[48:63], v[232:235], v[248:251], v[48:63]
	v_mfma_f32_32x32x16_bf16 v[32:47], v[232:235], v[252:255], v[32:47]
	ds_read_b128 v[228:231], v92 offset:4096
	v_mfma_f32_32x32x16_bf16 v[16:31], v[236:239], v[248:251], v[16:31]
	v_mfma_f32_32x32x16_bf16 v[0:15], v[236:239], v[252:255], v[0:15]
	s_add_u32 s101, s101, 2
	s_branch .Lgf_loop

; template <int EPI, int MI>
; DI void gemm_tile(const GemmDesc& g, int tm, int tn, char* smem) {
;     ...
;   const int rowA = wm * (32 * MI) + r, rowB = wn * 64 + r;
;   const int hk = hh ^ ((r & 7) ^ ((r >> 3) & 3));
;     ...
;   G_GLDS(0, 0);
;   asm volatile("s_waitcnt vmcnt(0)" ::: "memory");
;   __syncthreads();
;   for (int kt = 0; kt < nk; kt += 2) {
;     if (kt + 1 < nk) G_GLDS(kt + 1, 1);
;     G_COMPUTE(0);
;     asm volatile("s_waitcnt vmcnt(0)" ::: "memory");
;     __syncthreads();
;     if (kt + 1 < nk) {
;       if (kt + 2 < nk) G_GLDS(kt + 2, 0);
;       G_COMPUTE(1);
;       asm volatile("s_waitcnt vmcnt(0)" ::: "memory");
;       __syncthreads();
;     }
;   }
.Lge_loop:
	ds_read_b128 v[232:235], v162 offset:8192
	s_waitcnt lgkmcnt(2)
	v_mfma_f32_32x32x16_bf16 v[80:95], v[224:227], v[236:239], v[80:95]
	v_mfma_f32_32x32x16_bf16 v[64:79], v[224:227], v[240:243], v[64:79]
	s_mov_b64 s[16:17], 0x5872080
	s_add_u32 m0, s100, 0x6000
	v_lshl_add_u64 v[106:107], v[252:253], 0, s[16:17]
	global_load_lds_dwordx4 v[106:107], off
	s_mov_b64 s[16:17], 0x589e080
	s_add_u32 m0, s100, 0x7000
	v_lshl_add_u64 v[106:107], v[252:253], 0, s[16:17]
	global_load_lds_dwordx4 v[106:107], off
	ds_read_b128 v[244:247], v167 offset:49152
	ds_read_b128 v[248:251], v167 offset:53248
	ds_read_b128 v[224:227], v163
	s_waitcnt lgkmcnt(4)
	v_mfma_f32_32x32x16_bf16 v[48:63], v[228:231], v[236:239], v[48:63]
	v_mfma_f32_32x32x16_bf16 v[32:47], v[228:231], v[240:243], v[32:47]
	s_mov_b64 s[16:17], 0x58ca080
	s_add_u32 m0, s100, 0x8000
	v_lshl_add_u64 v[106:107], v[252:253], 0, s[16:17]
	global_load_lds_dwordx4 v[106:107], off
	s_mov_b64 s[16:17], 0x58f6080
	s_add_u32 m0, s100, 0x9000
	v_lshl_add_u64 v[106:107], v[252:253], 0, s[16:17]
	global_load_lds_dwordx4 v[106:107], off
	ds_read_b128 v[228:231], v163 offset:4096
	s_waitcnt lgkmcnt(4)
	v_mfma_f32_32x32x16_bf16 v[16:31], v[232:235], v[236:239], v[16:31]
	v_mfma_f32_32x32x16_bf16 v[0:15], v[232:235], v[240:243], v[0:15]
	s_mov_b64 s[16:17], 0x5922080
	s_add_u32 m0, s100, 0xa000
	v_lshl_add_u64 v[106:107], v[252:253], 0, s[16:17]
	global_load_lds_dwordx4 v[106:107], off
	s_mov_b64 s[16:17], 0x594e080
	s_add_u32 m0, s100, 0xb000
	v_lshl_add_u64 v[106:107], v[252:253], 0, s[16:17]
	global_load_lds_dwordx4 v[106:107], off
	v_lshl_add_u64 v[252:253], v[252:253], 0, s[4:5]
	ds_read_b128 v[232:235], v163 offset:8192
	s_waitcnt lgkmcnt(2)
	v_mfma_f32_32x32x16_bf16 v[80:95], v[224:227], v[244:247], v[80:95]
	v_mfma_f32_32x32x16_bf16 v[64:79], v[224:227], v[248:251], v[64:79]
	s_mov_b64 s[16:17], 0x1b80080
	s_add_u32 m0, s100, 0x10000
	v_lshl_add_u64 v[106:107], v[254:255], 0, s[16:17]
	global_load_lds_dwordx4 v[106:107], off
	s_mov_b64 s[16:17], 0x1bac080
	s_add_u32 m0, s100, 0x11000
	v_lshl_add_u64 v[106:107], v[254:255], 0, s[16:17]
	global_load_lds_dwordx4 v[106:107], off
	ds_read_b128 v[236:239], v168 offset:49152
	ds_read_b128 v[240:243], v168 offset:53248
	ds_read_b128 v[224:227], v164
	s_waitcnt lgkmcnt(4)
	v_mfma_f32_32x32x16_bf16 v[48:63], v[228:231], v[244:247], v[48:63]
	v_mfma_f32_32x32x16_bf16 v[32:47], v[228:231], v[248:251], v[32:47]
	s_mov_b64 s[16:17], 0x1bd8080
	s_add_u32 m0, s100, 0x12000
	v_lshl_add_u64 v[106:107], v[254:255], 0, s[16:17]
	global_load_lds_dwordx4 v[106:107], off
	s_mov_b64 s[16:17], 0x1c04080
	s_add_u32 m0, s100, 0x13000
	v_lshl_add_u64 v[106:107], v[254:255], 0, s[16:17]
	global_load_lds_dwordx4 v[106:107], off
	v_lshl_add_u64 v[254:255], v[254:255], 0, s[4:5]
	ds_read_b128 v[228:231], v164 offset:4096
	s_waitcnt lgkmcnt(4)
	v_mfma_f32_32x32x16_bf16 v[16:31], v[232:235], v[244:247], v[16:31]
	v_mfma_f32_32x32x16_bf16 v[0:15], v[232:235], v[248:251], v[0:15]
	ds_read_b128 v[232:235], v164 offset:8192
	s_waitcnt lgkmcnt(2)
	v_mfma_f32_32x32x16_bf16 v[80:95], v[224:227], v[236:239], v[80:95]
	v_mfma_f32_32x32x16_bf16 v[64:79], v[224:227], v[240:243], v[64:79]
	ds_read_b128 v[244:247], v169 offset:49152
	ds_read_b128 v[248:251], v169 offset:53248
	ds_read_b128 v[224:227], v165
	s_waitcnt lgkmcnt(4)
	v_mfma_f32_32x32x16_bf16 v[48:63], v[228:231], v[236:239], v[48:63]
	v_mfma_f32_32x32x16_bf16 v[32:47], v[228:231], v[240:243], v[32:47]
	ds_read_b128 v[228:231], v165 offset:4096
	s_waitcnt lgkmcnt(4)
	v_mfma_f32_32x32x16_bf16 v[16:31], v[232:235], v[236:239], v[16:31]
	v_mfma_f32_32x32x16_bf16 v[0:15], v[232:235], v[240:243], v[0:15]
	ds_read_b128 v[232:235], v165 offset:8192
	s_waitcnt lgkmcnt(2)
	v_mfma_f32_32x32x16_bf16 v[80:95], v[224:227], v[244:247], v[80:95]
	v_mfma_f32_32x32x16_bf16 v[64:79], v[224:227], v[248:251], v[64:79]
	s_waitcnt lgkmcnt(0)
	s_waitcnt vmcnt(0)
	s_barrier
	ds_read_b128 v[236:239], v170
	ds_read_b128 v[240:243], v170 offset:4096
	ds_read_b128 v[224:227], v162 offset:24576
	v_mfma_f32_32x32x16_bf16 v[48:63], v[228:231], v[244:247], v[48:63]
	v_mfma_f32_32x32x16_bf16 v[32:47], v[228:231], v[248:251], v[32:47]
	ds_read_b128 v[228:231], v162 offset:28672
	v_mfma_f32_32x32x16_bf16 v[16:31], v[232:235], v[244:247], v[16:31]
	v_mfma_f32_32x32x16_bf16 v[0:15], v[232:235], v[248:251], v[0:15]
	s_cmp_eq_u32 s15, 42
	s_cbranch_scc1 .Lge_last
; template <int EPI, int MI>
; DI void gemm_tile(const GemmDesc& g, int tm, int tn, char* smem) {
;     ...
;   const int rowA = wm * (32 * MI) + r, rowB = wn * 64 + r;
;   const int hk = hh ^ ((r & 7) ^ ((r >> 3) & 3));
;     ...
;   G_GLDS(0, 0);
;   asm volatile("s_waitcnt vmcnt(0)" ::: "memory");
;   __syncthreads();
;   for (int kt = 0; kt < nk; kt += 2) {
;     if (kt + 1 < nk) G_GLDS(kt + 1, 1);
;     G_COMPUTE(0);
;     asm volatile("s_waitcnt vmcnt(0)" ::: "memory");
;     __syncthreads();
;     if (kt + 1 < nk) {
;       if (kt + 2 < nk) G_GLDS(kt + 2, 0);
;       G_COMPUTE(1);
;       asm volatile("s_waitcnt vmcnt(0)" ::: "memory");
;       __syncthreads();
;     }
;   }
	ds_read_b128 v[232:235], v162 offset:32768
	s_waitcnt lgkmcnt(2)
	v_mfma_f32_32x32x16_bf16 v[80:95], v[224:227], v[236:239], v[80:95]
	v_mfma_f32_32x32x16_bf16 v[64:79], v[224:227], v[240:243], v[64:79]
	s_mov_b64 s[16:17], 0x5872080
	s_mov_b32 m0, s100
	v_lshl_add_u64 v[106:107], v[252:253], 0, s[16:17]
	global_load_lds_dwordx4 v[106:107], off
	s_mov_b64 s[16:17], 0x589e080
	s_add_u32 m0, s100, 0x1000
	v_lshl_add_u64 v[106:107], v[252:253], 0, s[16:17]
	global_load_lds_dwordx4 v[106:107], off
	ds_read_b128 v[244:247], v171
	ds_read_b128 v[248:251], v171 offset:4096
	ds_read_b128 v[224:227], v163 offset:24576
	s_waitcnt lgkmcnt(4)
	v_mfma_f32_32x32x16_bf16 v[48:63], v[228:231], v[236:239], v[48:63]
	v_mfma_f32_32x32x16_bf16 v[32:47], v[228:231], v[240:243], v[32:47]
	s_mov_b64 s[16:17], 0x58ca080
	s_add_u32 m0, s100, 0x2000
	v_lshl_add_u64 v[106:107], v[252:253], 0, s[16:17]
	global_load_lds_dwordx4 v[106:107], off
	s_mov_b64 s[16:17], 0x58f6080
	s_add_u32 m0, s100, 0x3000
	v_lshl_add_u64 v[106:107], v[252:253], 0, s[16:17]
	global_load_lds_dwordx4 v[106:107], off
	ds_read_b128 v[228:231], v163 offset:28672
	s_waitcnt lgkmcnt(4)
	v_mfma_f32_32x32x16_bf16 v[16:31], v[232:235], v[236:239], v[16:31]
	v_mfma_f32_32x32x16_bf16 v[0:15], v[232:235], v[240:243], v[0:15]
	s_mov_b64 s[16:17], 0x5922080
	s_add_u32 m0, s100, 0x4000
	v_lshl_add_u64 v[106:107], v[252:253], 0, s[16:17]
	global_load_lds_dwordx4 v[106:107], off
	s_mov_b64 s[16:17], 0x594e080
	s_add_u32 m0, s100, 0x5000
	v_lshl_add_u64 v[106:107], v[252:253], 0, s[16:17]
	global_load_lds_dwordx4 v[106:107], off
	v_lshl_add_u64 v[252:253], v[252:253], 0, s[4:5]
	ds_read_b128 v[232:235], v163 offset:32768
	s_waitcnt lgkmcnt(2)
	v_mfma_f32_32x32x16_bf16 v[80:95], v[224:227], v[244:247], v[80:95]
	v_mfma_f32_32x32x16_bf16 v[64:79], v[224:227], v[248:251], v[64:79]
	s_mov_b64 s[16:17], 0x1b80080
	s_add_u32 m0, s100, 0xc000
	v_lshl_add_u64 v[106:107], v[254:255], 0, s[16:17]
	global_load_lds_dwordx4 v[106:107], off
	s_mov_b64 s[16:17], 0x1bac080
	s_add_u32 m0, s100, 0xd000
	v_lshl_add_u64 v[106:107], v[254:255], 0, s[16:17]
	global_load_lds_dwordx4 v[106:107], off
	ds_read_b128 v[236:239], v172
	ds_read_b128 v[240:243], v172 offset:4096
	ds_read_b128 v[224:227], v164 offset:24576
	s_waitcnt lgkmcnt(4)
	v_mfma_f32_32x32x16_bf16 v[48:63], v[228:231], v[244:247], v[48:63]
	v_mfma_f32_32x32x16_bf16 v[32:47], v[228:231], v[248:251], v[32:47]
	s_mov_b64 s[16:17], 0x1bd8080
	s_add_u32 m0, s100, 0xe000
	v_lshl_add_u64 v[106:107], v[254:255], 0, s[16:17]
	global_load_lds_dwordx4 v[106:107], off
	s_mov_b64 s[16:17], 0x1c04080
	s_add_u32 m0, s100, 0xf000
	v_lshl_add_u64 v[106:107], v[254:255], 0, s[16:17]
	global_load_lds_dwordx4 v[106:107], off
	v_lshl_add_u64 v[254:255], v[254:255], 0, s[4:5]
	ds_read_b128 v[228:231], v164 offset:28672
	s_waitcnt lgkmcnt(4)
	v_mfma_f32_32x32x16_bf16 v[16:31], v[232:235], v[244:247], v[16:31]
	v_mfma_f32_32x32x16_bf16 v[0:15], v[232:235], v[248:251], v[0:15]
	ds_read_b128 v[232:235], v164 offset:32768
	s_waitcnt lgkmcnt(2)
	v_mfma_f32_32x32x16_bf16 v[80:95], v[224:227], v[236:239], v[80:95]
	v_mfma_f32_32x32x16_bf16 v[64:79], v[224:227], v[240:243], v[64:79]
	ds_read_b128 v[244:247], v173
	ds_read_b128 v[248:251], v173 offset:4096
	ds_read_b128 v[224:227], v165 offset:24576
	s_waitcnt lgkmcnt(4)
	v_mfma_f32_32x32x16_bf16 v[48:63], v[228:231], v[236:239], v[48:63]
	v_mfma_f32_32x32x16_bf16 v[32:47], v[228:231], v[240:243], v[32:47]
	ds_read_b128 v[228:231], v165 offset:28672
	s_waitcnt lgkmcnt(4)
	v_mfma_f32_32x32x16_bf16 v[16:31], v[232:235], v[236:239], v[16:31]
	v_mfma_f32_32x32x16_bf16 v[0:15], v[232:235], v[240:243], v[0:15]
	ds_read_b128 v[232:235], v165 offset:32768
	s_waitcnt lgkmcnt(2)
	v_mfma_f32_32x32x16_bf16 v[80:95], v[224:227], v[244:247], v[80:95]
	v_mfma_f32_32x32x16_bf16 v[64:79], v[224:227], v[248:251], v[64:79]
	s_waitcnt lgkmcnt(0)
	s_waitcnt vmcnt(0)
	s_barrier
	ds_read_b128 v[236:239], v166 offset:49152
	ds_read_b128 v[240:243], v166 offset:53248
	ds_read_b128 v[224:227], v162
	v_mfma_f32_32x32x16_bf16 v[48:63], v[228:231], v[244:247], v[48:63]
	v_mfma_f32_32x32x16_bf16 v[32:47], v[228:231], v[248:251], v[32:47]
	ds_read_b128 v[228:231], v162 offset:4096
	v_mfma_f32_32x32x16_bf16 v[16:31], v[232:235], v[244:247], v[16:31]
	v_mfma_f32_32x32x16_bf16 v[0:15], v[232:235], v[248:251], v[0:15]
	s_add_u32 s15, s15, 2
	s_branch .Lge_loop
